# P5 HGRN state scan: 64 steps fully unrolled, 16 loads of the next 8-step block in flight while the current block is processed (was one round trip per step)
# speedup vs baseline: 1.0421x; 1.0122x over previous
.Lscan_unrolled:
	s_mov_b64 s[22:23], 0x8000
	v_lshl_add_u64 v[40:41], v[0:1], 0, s[30:31]
	v_lshl_add_u64 v[42:43], v[40:41], 0, s[22:23]
	v_lshl_add_u64 v[44:45], v[42:43], 0, s[22:23]
	v_lshl_add_u64 v[46:47], v[44:45], 0, s[22:23]
	v_lshl_add_u64 v[48:49], v[46:47], 0, s[22:23]
	v_lshl_add_u64 v[50:51], v[48:49], 0, s[22:23]
	v_lshl_add_u64 v[52:53], v[50:51], 0, s[22:23]
	v_lshl_add_u64 v[54:55], v[52:53], 0, s[22:23]
	global_load_dword v16, v[40:41], off
	global_load_dword v17, v[42:43], off
	global_load_dword v18, v[44:45], off
	global_load_dword v19, v[46:47], off
	global_load_dword v20, v[48:49], off
	global_load_dword v21, v[50:51], off
	global_load_dword v22, v[52:53], off
	global_load_dword v23, v[54:55], off
	global_load_dwordx2 v[24:25], v[2:3], off offset:-3584
	global_load_dwordx2 v[26:27], v[2:3], off offset:-3072
	global_load_dwordx2 v[28:29], v[2:3], off offset:-2560
	global_load_dwordx2 v[30:31], v[2:3], off offset:-2048
	global_load_dwordx2 v[32:33], v[2:3], off offset:-1536
	global_load_dwordx2 v[34:35], v[2:3], off offset:-1024
	global_load_dwordx2 v[36:37], v[2:3], off offset:-512
	global_load_dwordx2 v[38:39], v[2:3], off
	s_add_u32 s30, s30, 0x40000
	s_addc_u32 s31, s31, 0
	v_lshl_add_u64 v[2:3], s[62:63], 4, v[2:3]
	v_lshl_add_u64 v[80:81], v[0:1], 0, s[30:31]
	v_lshl_add_u64 v[82:83], v[80:81], 0, s[22:23]
	v_lshl_add_u64 v[84:85], v[82:83], 0, s[22:23]
	v_lshl_add_u64 v[86:87], v[84:85], 0, s[22:23]
	v_lshl_add_u64 v[88:89], v[86:87], 0, s[22:23]
	v_lshl_add_u64 v[90:91], v[88:89], 0, s[22:23]
	v_lshl_add_u64 v[92:93], v[90:91], 0, s[22:23]
	v_lshl_add_u64 v[94:95], v[92:93], 0, s[22:23]
	global_load_dword v56, v[80:81], off
	global_load_dword v57, v[82:83], off
	global_load_dword v58, v[84:85], off
	global_load_dword v59, v[86:87], off
	global_load_dword v60, v[88:89], off
	global_load_dword v61, v[90:91], off
	global_load_dword v62, v[92:93], off
	global_load_dword v63, v[94:95], off
	global_load_dwordx2 v[64:65], v[2:3], off offset:-3584
	global_load_dwordx2 v[66:67], v[2:3], off offset:-3072
	global_load_dwordx2 v[68:69], v[2:3], off offset:-2560
	global_load_dwordx2 v[70:71], v[2:3], off offset:-2048
	global_load_dwordx2 v[72:73], v[2:3], off offset:-1536
	global_load_dwordx2 v[74:75], v[2:3], off offset:-1024
	global_load_dwordx2 v[76:77], v[2:3], off offset:-512
	global_load_dwordx2 v[78:79], v[2:3], off
	s_add_u32 s30, s30, 0x40000
	s_addc_u32 s31, s31, 0
	v_lshl_add_u64 v[2:3], s[62:63], 4, v[2:3]
	v_cvt_pk_bf16_f32 v12, v6, v7
	global_store_dword v[40:41], v12, off
	s_waitcnt vmcnt(24)
	v_lshlrev_b32_e32 v10, 16, v16
	v_and_b32_e32 v11, 0xffff0000, v16
	v_pk_fma_f32 v[6:7], v[6:7], v[24:25], v[10:11]
	v_cvt_pk_bf16_f32 v12, v6, v7
	global_store_dword v[42:43], v12, off
	s_waitcnt vmcnt(24)
	v_lshlrev_b32_e32 v10, 16, v17
	v_and_b32_e32 v11, 0xffff0000, v17
	v_pk_fma_f32 v[6:7], v[6:7], v[26:27], v[10:11]
	v_cvt_pk_bf16_f32 v12, v6, v7
	global_store_dword v[44:45], v12, off
	s_waitcnt vmcnt(24)
	v_lshlrev_b32_e32 v10, 16, v18
	v_and_b32_e32 v11, 0xffff0000, v18
	v_pk_fma_f32 v[6:7], v[6:7], v[28:29], v[10:11]
	v_cvt_pk_bf16_f32 v12, v6, v7
	global_store_dword v[46:47], v12, off
	s_waitcnt vmcnt(24)
	v_lshlrev_b32_e32 v10, 16, v19
	v_and_b32_e32 v11, 0xffff0000, v19
	v_pk_fma_f32 v[6:7], v[6:7], v[30:31], v[10:11]
	v_cvt_pk_bf16_f32 v12, v6, v7
	global_store_dword v[48:49], v12, off
	s_waitcnt vmcnt(24)
	v_lshlrev_b32_e32 v10, 16, v20
	v_and_b32_e32 v11, 0xffff0000, v20
	v_pk_fma_f32 v[6:7], v[6:7], v[32:33], v[10:11]
	v_cvt_pk_bf16_f32 v12, v6, v7
	global_store_dword v[50:51], v12, off
	s_waitcnt vmcnt(24)
	v_lshlrev_b32_e32 v10, 16, v21
	v_and_b32_e32 v11, 0xffff0000, v21
	v_pk_fma_f32 v[6:7], v[6:7], v[34:35], v[10:11]
	v_cvt_pk_bf16_f32 v12, v6, v7
	global_store_dword v[52:53], v12, off
	s_waitcnt vmcnt(24)
	v_lshlrev_b32_e32 v10, 16, v22
	v_and_b32_e32 v11, 0xffff0000, v22
	v_pk_fma_f32 v[6:7], v[6:7], v[36:37], v[10:11]
	v_cvt_pk_bf16_f32 v12, v6, v7
	global_store_dword v[54:55], v12, off
	s_waitcnt vmcnt(24)
	v_lshlrev_b32_e32 v10, 16, v23
	v_and_b32_e32 v11, 0xffff0000, v23
	v_pk_fma_f32 v[6:7], v[6:7], v[38:39], v[10:11]
	v_lshl_add_u64 v[40:41], v[0:1], 0, s[30:31]
	v_lshl_add_u64 v[42:43], v[40:41], 0, s[22:23]
	v_lshl_add_u64 v[44:45], v[42:43], 0, s[22:23]
	v_lshl_add_u64 v[46:47], v[44:45], 0, s[22:23]
	v_lshl_add_u64 v[48:49], v[46:47], 0, s[22:23]
	v_lshl_add_u64 v[50:51], v[48:49], 0, s[22:23]
	v_lshl_add_u64 v[52:53], v[50:51], 0, s[22:23]
	v_lshl_add_u64 v[54:55], v[52:53], 0, s[22:23]
	global_load_dword v16, v[40:41], off
	global_load_dword v17, v[42:43], off
	global_load_dword v18, v[44:45], off
	global_load_dword v19, v[46:47], off
	global_load_dword v20, v[48:49], off
	global_load_dword v21, v[50:51], off
	global_load_dword v22, v[52:53], off
	global_load_dword v23, v[54:55], off
	global_load_dwordx2 v[24:25], v[2:3], off offset:-3584
	global_load_dwordx2 v[26:27], v[2:3], off offset:-3072
	global_load_dwordx2 v[28:29], v[2:3], off offset:-2560
	global_load_dwordx2 v[30:31], v[2:3], off offset:-2048
	global_load_dwordx2 v[32:33], v[2:3], off offset:-1536
	global_load_dwordx2 v[34:35], v[2:3], off offset:-1024
	global_load_dwordx2 v[36:37], v[2:3], off offset:-512
	global_load_dwordx2 v[38:39], v[2:3], off
	s_add_u32 s30, s30, 0x40000
	s_addc_u32 s31, s31, 0
	v_lshl_add_u64 v[2:3], s[62:63], 4, v[2:3]
	v_cvt_pk_bf16_f32 v12, v6, v7
	global_store_dword v[80:81], v12, off
	s_waitcnt vmcnt(32)
	v_lshlrev_b32_e32 v10, 16, v56
	v_and_b32_e32 v11, 0xffff0000, v56
	v_pk_fma_f32 v[6:7], v[6:7], v[64:65], v[10:11]
	v_cvt_pk_bf16_f32 v12, v6, v7
	global_store_dword v[82:83], v12, off
	s_waitcnt vmcnt(32)
	v_lshlrev_b32_e32 v10, 16, v57
	v_and_b32_e32 v11, 0xffff0000, v57
	v_pk_fma_f32 v[6:7], v[6:7], v[66:67], v[10:11]
	v_cvt_pk_bf16_f32 v12, v6, v7
	global_store_dword v[84:85], v12, off
	s_waitcnt vmcnt(32)
	v_lshlrev_b32_e32 v10, 16, v58
	v_and_b32_e32 v11, 0xffff0000, v58
	v_pk_fma_f32 v[6:7], v[6:7], v[68:69], v[10:11]
	v_cvt_pk_bf16_f32 v12, v6, v7
	global_store_dword v[86:87], v12, off
	s_waitcnt vmcnt(32)
	v_lshlrev_b32_e32 v10, 16, v59
	v_and_b32_e32 v11, 0xffff0000, v59
	v_pk_fma_f32 v[6:7], v[6:7], v[70:71], v[10:11]
	v_cvt_pk_bf16_f32 v12, v6, v7
	global_store_dword v[88:89], v12, off
	s_waitcnt vmcnt(32)
	v_lshlrev_b32_e32 v10, 16, v60
	v_and_b32_e32 v11, 0xffff0000, v60
	v_pk_fma_f32 v[6:7], v[6:7], v[72:73], v[10:11]
	v_cvt_pk_bf16_f32 v12, v6, v7
	global_store_dword v[90:91], v12, off
	s_waitcnt vmcnt(32)
	v_lshlrev_b32_e32 v10, 16, v61
	v_and_b32_e32 v11, 0xffff0000, v61
	v_pk_fma_f32 v[6:7], v[6:7], v[74:75], v[10:11]
	v_cvt_pk_bf16_f32 v12, v6, v7
	global_store_dword v[92:93], v12, off
	s_waitcnt vmcnt(32)
	v_lshlrev_b32_e32 v10, 16, v62
	v_and_b32_e32 v11, 0xffff0000, v62
	v_pk_fma_f32 v[6:7], v[6:7], v[76:77], v[10:11]
	v_cvt_pk_bf16_f32 v12, v6, v7
	global_store_dword v[94:95], v12, off
	s_waitcnt vmcnt(32)
	v_lshlrev_b32_e32 v10, 16, v63
	v_and_b32_e32 v11, 0xffff0000, v63
	v_pk_fma_f32 v[6:7], v[6:7], v[78:79], v[10:11]
	v_lshl_add_u64 v[80:81], v[0:1], 0, s[30:31]
	v_lshl_add_u64 v[82:83], v[80:81], 0, s[22:23]
	v_lshl_add_u64 v[84:85], v[82:83], 0, s[22:23]
	v_lshl_add_u64 v[86:87], v[84:85], 0, s[22:23]
	v_lshl_add_u64 v[88:89], v[86:87], 0, s[22:23]
	v_lshl_add_u64 v[90:91], v[88:89], 0, s[22:23]
	v_lshl_add_u64 v[92:93], v[90:91], 0, s[22:23]
	v_lshl_add_u64 v[94:95], v[92:93], 0, s[22:23]
	global_load_dword v56, v[80:81], off
	global_load_dword v57, v[82:83], off
	global_load_dword v58, v[84:85], off
	global_load_dword v59, v[86:87], off
	global_load_dword v60, v[88:89], off
	global_load_dword v61, v[90:91], off
	global_load_dword v62, v[92:93], off
	global_load_dword v63, v[94:95], off
	global_load_dwordx2 v[64:65], v[2:3], off offset:-3584
	global_load_dwordx2 v[66:67], v[2:3], off offset:-3072
	global_load_dwordx2 v[68:69], v[2:3], off offset:-2560
	global_load_dwordx2 v[70:71], v[2:3], off offset:-2048
	global_load_dwordx2 v[72:73], v[2:3], off offset:-1536
	global_load_dwordx2 v[74:75], v[2:3], off offset:-1024
	global_load_dwordx2 v[76:77], v[2:3], off offset:-512
	global_load_dwordx2 v[78:79], v[2:3], off
	s_add_u32 s30, s30, 0x40000
	s_addc_u32 s31, s31, 0
	v_lshl_add_u64 v[2:3], s[62:63], 4, v[2:3]
	v_cvt_pk_bf16_f32 v12, v6, v7
	global_store_dword v[40:41], v12, off
	s_waitcnt vmcnt(32)
	v_lshlrev_b32_e32 v10, 16, v16
	v_and_b32_e32 v11, 0xffff0000, v16
	v_pk_fma_f32 v[6:7], v[6:7], v[24:25], v[10:11]
	v_cvt_pk_bf16_f32 v12, v6, v7
	global_store_dword v[42:43], v12, off
	s_waitcnt vmcnt(32)
	v_lshlrev_b32_e32 v10, 16, v17
	v_and_b32_e32 v11, 0xffff0000, v17
	v_pk_fma_f32 v[6:7], v[6:7], v[26:27], v[10:11]
	v_cvt_pk_bf16_f32 v12, v6, v7
	global_store_dword v[44:45], v12, off
	s_waitcnt vmcnt(32)
	v_lshlrev_b32_e32 v10, 16, v18
	v_and_b32_e32 v11, 0xffff0000, v18
	v_pk_fma_f32 v[6:7], v[6:7], v[28:29], v[10:11]
	v_cvt_pk_bf16_f32 v12, v6, v7
	global_store_dword v[46:47], v12, off
	s_waitcnt vmcnt(32)
	v_lshlrev_b32_e32 v10, 16, v19
	v_and_b32_e32 v11, 0xffff0000, v19
	v_pk_fma_f32 v[6:7], v[6:7], v[30:31], v[10:11]
	v_cvt_pk_bf16_f32 v12, v6, v7
	global_store_dword v[48:49], v12, off
	s_waitcnt vmcnt(32)
	v_lshlrev_b32_e32 v10, 16, v20
	v_and_b32_e32 v11, 0xffff0000, v20
	v_pk_fma_f32 v[6:7], v[6:7], v[32:33], v[10:11]
	v_cvt_pk_bf16_f32 v12, v6, v7
	global_store_dword v[50:51], v12, off
	s_waitcnt vmcnt(32)
	v_lshlrev_b32_e32 v10, 16, v21
	v_and_b32_e32 v11, 0xffff0000, v21
	v_pk_fma_f32 v[6:7], v[6:7], v[34:35], v[10:11]
	v_cvt_pk_bf16_f32 v12, v6, v7
	global_store_dword v[52:53], v12, off
	s_waitcnt vmcnt(32)
	v_lshlrev_b32_e32 v10, 16, v22
	v_and_b32_e32 v11, 0xffff0000, v22
	v_pk_fma_f32 v[6:7], v[6:7], v[36:37], v[10:11]
	v_cvt_pk_bf16_f32 v12, v6, v7
	global_store_dword v[54:55], v12, off
	s_waitcnt vmcnt(32)
	v_lshlrev_b32_e32 v10, 16, v23
	v_and_b32_e32 v11, 0xffff0000, v23
	v_pk_fma_f32 v[6:7], v[6:7], v[38:39], v[10:11]
	v_lshl_add_u64 v[40:41], v[0:1], 0, s[30:31]
	v_lshl_add_u64 v[42:43], v[40:41], 0, s[22:23]
	v_lshl_add_u64 v[44:45], v[42:43], 0, s[22:23]
	v_lshl_add_u64 v[46:47], v[44:45], 0, s[22:23]
	v_lshl_add_u64 v[48:49], v[46:47], 0, s[22:23]
	v_lshl_add_u64 v[50:51], v[48:49], 0, s[22:23]
	v_lshl_add_u64 v[52:53], v[50:51], 0, s[22:23]
	v_lshl_add_u64 v[54:55], v[52:53], 0, s[22:23]
	global_load_dword v16, v[40:41], off
	global_load_dword v17, v[42:43], off
	global_load_dword v18, v[44:45], off
	global_load_dword v19, v[46:47], off
	global_load_dword v20, v[48:49], off
	global_load_dword v21, v[50:51], off
	global_load_dword v22, v[52:53], off
	global_load_dword v23, v[54:55], off
	global_load_dwordx2 v[24:25], v[2:3], off offset:-3584
	global_load_dwordx2 v[26:27], v[2:3], off offset:-3072
	global_load_dwordx2 v[28:29], v[2:3], off offset:-2560
	global_load_dwordx2 v[30:31], v[2:3], off offset:-2048
	global_load_dwordx2 v[32:33], v[2:3], off offset:-1536
	global_load_dwordx2 v[34:35], v[2:3], off offset:-1024
	global_load_dwordx2 v[36:37], v[2:3], off offset:-512
	global_load_dwordx2 v[38:39], v[2:3], off
	s_add_u32 s30, s30, 0x40000
	s_addc_u32 s31, s31, 0
	v_lshl_add_u64 v[2:3], s[62:63], 4, v[2:3]
	v_cvt_pk_bf16_f32 v12, v6, v7
	global_store_dword v[80:81], v12, off
	s_waitcnt vmcnt(32)
	v_lshlrev_b32_e32 v10, 16, v56
	v_and_b32_e32 v11, 0xffff0000, v56
	v_pk_fma_f32 v[6:7], v[6:7], v[64:65], v[10:11]
	v_cvt_pk_bf16_f32 v12, v6, v7
	global_store_dword v[82:83], v12, off
	s_waitcnt vmcnt(32)
	v_lshlrev_b32_e32 v10, 16, v57
	v_and_b32_e32 v11, 0xffff0000, v57
	v_pk_fma_f32 v[6:7], v[6:7], v[66:67], v[10:11]
	v_cvt_pk_bf16_f32 v12, v6, v7
	global_store_dword v[84:85], v12, off
	s_waitcnt vmcnt(32)
	v_lshlrev_b32_e32 v10, 16, v58
	v_and_b32_e32 v11, 0xffff0000, v58
	v_pk_fma_f32 v[6:7], v[6:7], v[68:69], v[10:11]
	v_cvt_pk_bf16_f32 v12, v6, v7
	global_store_dword v[86:87], v12, off
	s_waitcnt vmcnt(32)
	v_lshlrev_b32_e32 v10, 16, v59
	v_and_b32_e32 v11, 0xffff0000, v59
	v_pk_fma_f32 v[6:7], v[6:7], v[70:71], v[10:11]
	v_cvt_pk_bf16_f32 v12, v6, v7
	global_store_dword v[88:89], v12, off
	s_waitcnt vmcnt(32)
	v_lshlrev_b32_e32 v10, 16, v60
	v_and_b32_e32 v11, 0xffff0000, v60
	v_pk_fma_f32 v[6:7], v[6:7], v[72:73], v[10:11]
	v_cvt_pk_bf16_f32 v12, v6, v7
	global_store_dword v[90:91], v12, off
	s_waitcnt vmcnt(32)
	v_lshlrev_b32_e32 v10, 16, v61
	v_and_b32_e32 v11, 0xffff0000, v61
	v_pk_fma_f32 v[6:7], v[6:7], v[74:75], v[10:11]
	v_cvt_pk_bf16_f32 v12, v6, v7
	global_store_dword v[92:93], v12, off
	s_waitcnt vmcnt(32)
	v_lshlrev_b32_e32 v10, 16, v62
	v_and_b32_e32 v11, 0xffff0000, v62
	v_pk_fma_f32 v[6:7], v[6:7], v[76:77], v[10:11]
	v_cvt_pk_bf16_f32 v12, v6, v7
	global_store_dword v[94:95], v12, off
	s_waitcnt vmcnt(32)
	v_lshlrev_b32_e32 v10, 16, v63
	v_and_b32_e32 v11, 0xffff0000, v63
	v_pk_fma_f32 v[6:7], v[6:7], v[78:79], v[10:11]
	v_lshl_add_u64 v[80:81], v[0:1], 0, s[30:31]
	v_lshl_add_u64 v[82:83], v[80:81], 0, s[22:23]
	v_lshl_add_u64 v[84:85], v[82:83], 0, s[22:23]
	v_lshl_add_u64 v[86:87], v[84:85], 0, s[22:23]
	v_lshl_add_u64 v[88:89], v[86:87], 0, s[22:23]
	v_lshl_add_u64 v[90:91], v[88:89], 0, s[22:23]
	v_lshl_add_u64 v[92:93], v[90:91], 0, s[22:23]
	v_lshl_add_u64 v[94:95], v[92:93], 0, s[22:23]
	global_load_dword v56, v[80:81], off
	global_load_dword v57, v[82:83], off
	global_load_dword v58, v[84:85], off
	global_load_dword v59, v[86:87], off
	global_load_dword v60, v[88:89], off
	global_load_dword v61, v[90:91], off
	global_load_dword v62, v[92:93], off
	global_load_dword v63, v[94:95], off
	global_load_dwordx2 v[64:65], v[2:3], off offset:-3584
	global_load_dwordx2 v[66:67], v[2:3], off offset:-3072
	global_load_dwordx2 v[68:69], v[2:3], off offset:-2560
	global_load_dwordx2 v[70:71], v[2:3], off offset:-2048
	global_load_dwordx2 v[72:73], v[2:3], off offset:-1536
	global_load_dwordx2 v[74:75], v[2:3], off offset:-1024
	global_load_dwordx2 v[76:77], v[2:3], off offset:-512
	global_load_dwordx2 v[78:79], v[2:3], off
	s_add_u32 s30, s30, 0x40000
	s_addc_u32 s31, s31, 0
	v_lshl_add_u64 v[2:3], s[62:63], 4, v[2:3]
	v_cvt_pk_bf16_f32 v12, v6, v7
	global_store_dword v[40:41], v12, off
	s_waitcnt vmcnt(32)
	v_lshlrev_b32_e32 v10, 16, v16
	v_and_b32_e32 v11, 0xffff0000, v16
	v_pk_fma_f32 v[6:7], v[6:7], v[24:25], v[10:11]
	v_cvt_pk_bf16_f32 v12, v6, v7
	global_store_dword v[42:43], v12, off
	s_waitcnt vmcnt(32)
	v_lshlrev_b32_e32 v10, 16, v17
	v_and_b32_e32 v11, 0xffff0000, v17
	v_pk_fma_f32 v[6:7], v[6:7], v[26:27], v[10:11]
	v_cvt_pk_bf16_f32 v12, v6, v7
	global_store_dword v[44:45], v12, off
	s_waitcnt vmcnt(32)
	v_lshlrev_b32_e32 v10, 16, v18
	v_and_b32_e32 v11, 0xffff0000, v18
	v_pk_fma_f32 v[6:7], v[6:7], v[28:29], v[10:11]
	v_cvt_pk_bf16_f32 v12, v6, v7
	global_store_dword v[46:47], v12, off
	s_waitcnt vmcnt(32)
	v_lshlrev_b32_e32 v10, 16, v19
	v_and_b32_e32 v11, 0xffff0000, v19
	v_pk_fma_f32 v[6:7], v[6:7], v[30:31], v[10:11]
	v_cvt_pk_bf16_f32 v12, v6, v7
	global_store_dword v[48:49], v12, off
	s_waitcnt vmcnt(32)
	v_lshlrev_b32_e32 v10, 16, v20
	v_and_b32_e32 v11, 0xffff0000, v20
	v_pk_fma_f32 v[6:7], v[6:7], v[32:33], v[10:11]
	v_cvt_pk_bf16_f32 v12, v6, v7
	global_store_dword v[50:51], v12, off
	s_waitcnt vmcnt(32)
	v_lshlrev_b32_e32 v10, 16, v21
	v_and_b32_e32 v11, 0xffff0000, v21
	v_pk_fma_f32 v[6:7], v[6:7], v[34:35], v[10:11]
	v_cvt_pk_bf16_f32 v12, v6, v7
	global_store_dword v[52:53], v12, off
	s_waitcnt vmcnt(32)
	v_lshlrev_b32_e32 v10, 16, v22
	v_and_b32_e32 v11, 0xffff0000, v22
	v_pk_fma_f32 v[6:7], v[6:7], v[36:37], v[10:11]
	v_cvt_pk_bf16_f32 v12, v6, v7
	global_store_dword v[54:55], v12, off
	s_waitcnt vmcnt(32)
	v_lshlrev_b32_e32 v10, 16, v23
	v_and_b32_e32 v11, 0xffff0000, v23
	v_pk_fma_f32 v[6:7], v[6:7], v[38:39], v[10:11]
	v_lshl_add_u64 v[40:41], v[0:1], 0, s[30:31]
	v_lshl_add_u64 v[42:43], v[40:41], 0, s[22:23]
	v_lshl_add_u64 v[44:45], v[42:43], 0, s[22:23]
	v_lshl_add_u64 v[46:47], v[44:45], 0, s[22:23]
	v_lshl_add_u64 v[48:49], v[46:47], 0, s[22:23]
	v_lshl_add_u64 v[50:51], v[48:49], 0, s[22:23]
	v_lshl_add_u64 v[52:53], v[50:51], 0, s[22:23]
	v_lshl_add_u64 v[54:55], v[52:53], 0, s[22:23]
	global_load_dword v16, v[40:41], off
	global_load_dword v17, v[42:43], off
	global_load_dword v18, v[44:45], off
	global_load_dword v19, v[46:47], off
	global_load_dword v20, v[48:49], off
	global_load_dword v21, v[50:51], off
	global_load_dword v22, v[52:53], off
	global_load_dword v23, v[54:55], off
	global_load_dwordx2 v[24:25], v[2:3], off offset:-3584
	global_load_dwordx2 v[26:27], v[2:3], off offset:-3072
	global_load_dwordx2 v[28:29], v[2:3], off offset:-2560
	global_load_dwordx2 v[30:31], v[2:3], off offset:-2048
	global_load_dwordx2 v[32:33], v[2:3], off offset:-1536
	global_load_dwordx2 v[34:35], v[2:3], off offset:-1024
	global_load_dwordx2 v[36:37], v[2:3], off offset:-512
	global_load_dwordx2 v[38:39], v[2:3], off
	s_add_u32 s30, s30, 0x40000
	s_addc_u32 s31, s31, 0
	v_lshl_add_u64 v[2:3], s[62:63], 4, v[2:3]
	v_cvt_pk_bf16_f32 v12, v6, v7
	global_store_dword v[80:81], v12, off
	s_waitcnt vmcnt(32)
	v_lshlrev_b32_e32 v10, 16, v56
	v_and_b32_e32 v11, 0xffff0000, v56
	v_pk_fma_f32 v[6:7], v[6:7], v[64:65], v[10:11]
	v_cvt_pk_bf16_f32 v12, v6, v7
	global_store_dword v[82:83], v12, off
	s_waitcnt vmcnt(32)
	v_lshlrev_b32_e32 v10, 16, v57
	v_and_b32_e32 v11, 0xffff0000, v57
	v_pk_fma_f32 v[6:7], v[6:7], v[66:67], v[10:11]
	v_cvt_pk_bf16_f32 v12, v6, v7
	global_store_dword v[84:85], v12, off
	s_waitcnt vmcnt(32)
	v_lshlrev_b32_e32 v10, 16, v58
	v_and_b32_e32 v11, 0xffff0000, v58
	v_pk_fma_f32 v[6:7], v[6:7], v[68:69], v[10:11]
	v_cvt_pk_bf16_f32 v12, v6, v7
	global_store_dword v[86:87], v12, off
	s_waitcnt vmcnt(32)
	v_lshlrev_b32_e32 v10, 16, v59
	v_and_b32_e32 v11, 0xffff0000, v59
	v_pk_fma_f32 v[6:7], v[6:7], v[70:71], v[10:11]
	v_cvt_pk_bf16_f32 v12, v6, v7
	global_store_dword v[88:89], v12, off
	s_waitcnt vmcnt(32)
	v_lshlrev_b32_e32 v10, 16, v60
	v_and_b32_e32 v11, 0xffff0000, v60
	v_pk_fma_f32 v[6:7], v[6:7], v[72:73], v[10:11]
	v_cvt_pk_bf16_f32 v12, v6, v7
	global_store_dword v[90:91], v12, off
	s_waitcnt vmcnt(32)
	v_lshlrev_b32_e32 v10, 16, v61
	v_and_b32_e32 v11, 0xffff0000, v61
	v_pk_fma_f32 v[6:7], v[6:7], v[74:75], v[10:11]
	v_cvt_pk_bf16_f32 v12, v6, v7
	global_store_dword v[92:93], v12, off
	s_waitcnt vmcnt(32)
	v_lshlrev_b32_e32 v10, 16, v62
	v_and_b32_e32 v11, 0xffff0000, v62
	v_pk_fma_f32 v[6:7], v[6:7], v[76:77], v[10:11]
	v_cvt_pk_bf16_f32 v12, v6, v7
	global_store_dword v[94:95], v12, off
	s_waitcnt vmcnt(32)
	v_lshlrev_b32_e32 v10, 16, v63
	v_and_b32_e32 v11, 0xffff0000, v63
	v_pk_fma_f32 v[6:7], v[6:7], v[78:79], v[10:11]
	v_lshl_add_u64 v[80:81], v[0:1], 0, s[30:31]
	v_lshl_add_u64 v[82:83], v[80:81], 0, s[22:23]
	v_lshl_add_u64 v[84:85], v[82:83], 0, s[22:23]
	v_lshl_add_u64 v[86:87], v[84:85], 0, s[22:23]
	v_lshl_add_u64 v[88:89], v[86:87], 0, s[22:23]
	v_lshl_add_u64 v[90:91], v[88:89], 0, s[22:23]
	v_lshl_add_u64 v[92:93], v[90:91], 0, s[22:23]
	v_lshl_add_u64 v[94:95], v[92:93], 0, s[22:23]
	global_load_dword v56, v[80:81], off
	global_load_dword v57, v[82:83], off
	global_load_dword v58, v[84:85], off
	global_load_dword v59, v[86:87], off
	global_load_dword v60, v[88:89], off
	global_load_dword v61, v[90:91], off
	global_load_dword v62, v[92:93], off
	global_load_dword v63, v[94:95], off
	global_load_dwordx2 v[64:65], v[2:3], off offset:-3584
	global_load_dwordx2 v[66:67], v[2:3], off offset:-3072
	global_load_dwordx2 v[68:69], v[2:3], off offset:-2560
	global_load_dwordx2 v[70:71], v[2:3], off offset:-2048
	global_load_dwordx2 v[72:73], v[2:3], off offset:-1536
	global_load_dwordx2 v[74:75], v[2:3], off offset:-1024
	global_load_dwordx2 v[76:77], v[2:3], off offset:-512
	global_load_dwordx2 v[78:79], v[2:3], off
	s_add_u32 s30, s30, 0x40000
	s_addc_u32 s31, s31, 0
	v_lshl_add_u64 v[2:3], s[62:63], 4, v[2:3]
	v_cvt_pk_bf16_f32 v12, v6, v7
	global_store_dword v[40:41], v12, off
	s_waitcnt vmcnt(32)
	v_lshlrev_b32_e32 v10, 16, v16
	v_and_b32_e32 v11, 0xffff0000, v16
	v_pk_fma_f32 v[6:7], v[6:7], v[24:25], v[10:11]
	v_cvt_pk_bf16_f32 v12, v6, v7
	global_store_dword v[42:43], v12, off
	s_waitcnt vmcnt(32)
	v_lshlrev_b32_e32 v10, 16, v17
	v_and_b32_e32 v11, 0xffff0000, v17
	v_pk_fma_f32 v[6:7], v[6:7], v[26:27], v[10:11]
	v_cvt_pk_bf16_f32 v12, v6, v7
	global_store_dword v[44:45], v12, off
	s_waitcnt vmcnt(32)
	v_lshlrev_b32_e32 v10, 16, v18
	v_and_b32_e32 v11, 0xffff0000, v18
	v_pk_fma_f32 v[6:7], v[6:7], v[28:29], v[10:11]
	v_cvt_pk_bf16_f32 v12, v6, v7
	global_store_dword v[46:47], v12, off
	s_waitcnt vmcnt(32)
	v_lshlrev_b32_e32 v10, 16, v19
	v_and_b32_e32 v11, 0xffff0000, v19
	v_pk_fma_f32 v[6:7], v[6:7], v[30:31], v[10:11]
	v_cvt_pk_bf16_f32 v12, v6, v7
	global_store_dword v[48:49], v12, off
	s_waitcnt vmcnt(32)
	v_lshlrev_b32_e32 v10, 16, v20
	v_and_b32_e32 v11, 0xffff0000, v20
	v_pk_fma_f32 v[6:7], v[6:7], v[32:33], v[10:11]
	v_cvt_pk_bf16_f32 v12, v6, v7
	global_store_dword v[50:51], v12, off
	s_waitcnt vmcnt(32)
	v_lshlrev_b32_e32 v10, 16, v21
	v_and_b32_e32 v11, 0xffff0000, v21
	v_pk_fma_f32 v[6:7], v[6:7], v[34:35], v[10:11]
	v_cvt_pk_bf16_f32 v12, v6, v7
	global_store_dword v[52:53], v12, off
	s_waitcnt vmcnt(32)
	v_lshlrev_b32_e32 v10, 16, v22
	v_and_b32_e32 v11, 0xffff0000, v22
	v_pk_fma_f32 v[6:7], v[6:7], v[36:37], v[10:11]
	v_cvt_pk_bf16_f32 v12, v6, v7
	global_store_dword v[54:55], v12, off
	s_waitcnt vmcnt(32)
	v_lshlrev_b32_e32 v10, 16, v23
	v_and_b32_e32 v11, 0xffff0000, v23
	v_pk_fma_f32 v[6:7], v[6:7], v[38:39], v[10:11]
	v_cvt_pk_bf16_f32 v12, v6, v7
	global_store_dword v[80:81], v12, off
	s_waitcnt vmcnt(16)
	v_lshlrev_b32_e32 v10, 16, v56
	v_and_b32_e32 v11, 0xffff0000, v56
	v_pk_fma_f32 v[6:7], v[6:7], v[64:65], v[10:11]
	v_cvt_pk_bf16_f32 v12, v6, v7
	global_store_dword v[82:83], v12, off
	s_waitcnt vmcnt(16)
	v_lshlrev_b32_e32 v10, 16, v57
	v_and_b32_e32 v11, 0xffff0000, v57
	v_pk_fma_f32 v[6:7], v[6:7], v[66:67], v[10:11]
	v_cvt_pk_bf16_f32 v12, v6, v7
	global_store_dword v[84:85], v12, off
	s_waitcnt vmcnt(16)
	v_lshlrev_b32_e32 v10, 16, v58
	v_and_b32_e32 v11, 0xffff0000, v58
	v_pk_fma_f32 v[6:7], v[6:7], v[68:69], v[10:11]
	v_cvt_pk_bf16_f32 v12, v6, v7
	global_store_dword v[86:87], v12, off
	s_waitcnt vmcnt(16)
	v_lshlrev_b32_e32 v10, 16, v59
	v_and_b32_e32 v11, 0xffff0000, v59
	v_pk_fma_f32 v[6:7], v[6:7], v[70:71], v[10:11]
	v_cvt_pk_bf16_f32 v12, v6, v7
	global_store_dword v[88:89], v12, off
	s_waitcnt vmcnt(16)
	v_lshlrev_b32_e32 v10, 16, v60
	v_and_b32_e32 v11, 0xffff0000, v60
	v_pk_fma_f32 v[6:7], v[6:7], v[72:73], v[10:11]
	v_cvt_pk_bf16_f32 v12, v6, v7
	global_store_dword v[90:91], v12, off
	s_waitcnt vmcnt(16)
	v_lshlrev_b32_e32 v10, 16, v61
	v_and_b32_e32 v11, 0xffff0000, v61
	v_pk_fma_f32 v[6:7], v[6:7], v[74:75], v[10:11]
	v_cvt_pk_bf16_f32 v12, v6, v7
	global_store_dword v[92:93], v12, off
	s_waitcnt vmcnt(16)
	v_lshlrev_b32_e32 v10, 16, v62
	v_and_b32_e32 v11, 0xffff0000, v62
	v_pk_fma_f32 v[6:7], v[6:7], v[76:77], v[10:11]
	v_cvt_pk_bf16_f32 v12, v6, v7
	global_store_dword v[94:95], v12, off
	s_waitcnt vmcnt(16)
	v_lshlrev_b32_e32 v10, 16, v63
	v_and_b32_e32 v11, 0xffff0000, v63
	v_pk_fma_f32 v[6:7], v[6:7], v[78:79], v[10:11]
	v_add_u32_e32 v8, s76, v8
	s_mov_b32 s1, 0x1ffff
	v_cmp_lt_i32_e32 vcc, s1, v8
	s_or_b64 s[24:25], vcc, s[24:25]
	s_andn2_b64 exec, exec, s[24:25]
	s_cbranch_execnz .LBB0_1477
